# adds: phase_prep adaLN GEMV loop unrolled 4x with weight loads prefetched 3 iterations ahead (16 loads in flight per thread instead of 4, counted vmcnt)
# speedup vs baseline: 1.0004x; 1.0004x over previous
; #define LAS __attribute__((address_space(3)))
; DI void phase_prep(const Params& p, LAS unsigned char* lds) {
;     ...
;     for (int it = bid; it < 4 * 144; it += nb) {
;       const int l = it / 144, col0 = (it % 144) * 64, ks = tid >> 6, col = tid & 63;
;       const float* wp = p.w_ada + ((size_t)l * 1024 + ks * 128) * NMODW + col0 + col;
;       float a[17];
; #pragma unroll
;       for (int r = 0; r < 17; ++r) a[r] = 0.f;
; #pragma unroll 4
;       for (int k = 0; k < 128; ++k) { const float wv = wp[(size_t)k * NMODW]; const LAS float* sp = sc + (ks * 128 + k) * 20;
;         const f32x4 s0 = *(const LAS f32x4*)sp, s1 = *(const LAS f32x4*)(sp + 4), s2 = *(const LAS f32x4*)(sp + 8), s3 = *(const LAS f32x4*)(sp + 12); const float s16 = sp[16];
; #pragma unroll
;         for (int e = 0; e < 4; ++e) { a[e] += s0[e] * wv; a[4 + e] += s1[e] * wv; a[8 + e] += s2[e] * wv; a[12 + e] += s3[e] * wv; }
;         a[16] += s16 * wv; }
.LBB0_301:
	s_mul_hi_i32 s4, s16, 0x38e38e39
	s_lshr_b32 s5, s4, 31
	s_ashr_i32 s4, s4, 5
	s_add_i32 s4, s4, s5
	s_mul_i32 s5, s4, 0x90
	s_sub_i32 s5, s16, s5
	s_lshl_b32 s6, s5, 6
	s_ashr_i32 s5, s4, 31
	s_lshl_b64 s[8:9], s[4:5], 10
	v_lshl_add_u64 v[2:3], s[8:9], 0, v[20:21]
	v_mad_u64_u32 v[4:5], s[8:9], v2, s13, v[26:27]
	v_mad_i32_i24 v5, v3, s13, v5
	s_ashr_i32 s7, s6, 31
	v_lshl_add_u64 v[2:3], s[6:7], 2, v[4:5]
	v_lshl_add_u64 v[28:29], v[2:3], 0, v[22:23]
	s_mov_b64 s[8:9], 0
	v_mov_b32_e32 v49, v1
	v_mov_b32_e32 v48, 0
	v_mov_b32_e32 v30, 0
	v_mov_b32_e32 v31, v21
	v_mov_b32_e32 v32, 0
	v_mov_b32_e32 v33, v21
	v_mov_b32_e32 v34, 0
	v_mov_b32_e32 v35, v21
	v_mov_b32_e32 v36, 0
	v_mov_b32_e32 v37, v21
	v_mov_b32_e32 v38, 0
	v_mov_b32_e32 v39, v21
	v_mov_b32_e32 v40, 0
	v_mov_b32_e32 v41, v21
	v_mov_b32_e32 v42, 0
	v_mov_b32_e32 v43, v21
	v_mov_b32_e32 v44, 0
	v_mov_b32_e32 v45, v21
	v_lshl_add_u64 v[154:155], v[28:29], 0, s[8:9]
	s_add_u32 s100, s8, s13
	s_addc_u32 s101, s9, 0
	v_lshl_add_u64 v[156:157], v[28:29], 0, s[100:101]
	s_add_u32 s100, s8, s14
	s_addc_u32 s101, s9, 0
	v_lshl_add_u64 v[158:159], v[28:29], 0, s[100:101]
	s_add_u32 s100, s8, s15
	s_addc_u32 s101, s9, 0
	v_lshl_add_u64 v[160:161], v[28:29], 0, s[100:101]
	global_load_dword v104, v[154:155], off
	global_load_dword v106, v[156:157], off
	global_load_dword v110, v[158:159], off
	global_load_dword v112, v[160:161], off
	s_add_u32 s8, s8, 0x24000
	s_addc_u32 s9, s9, 0
	v_lshl_add_u64 v[154:155], v[28:29], 0, s[8:9]
	s_add_u32 s100, s8, s13
	s_addc_u32 s101, s9, 0
	v_lshl_add_u64 v[156:157], v[28:29], 0, s[100:101]
	s_add_u32 s100, s8, s14
	s_addc_u32 s101, s9, 0
	v_lshl_add_u64 v[158:159], v[28:29], 0, s[100:101]
	s_add_u32 s100, s8, s15
	s_addc_u32 s101, s9, 0
	v_lshl_add_u64 v[160:161], v[28:29], 0, s[100:101]
	global_load_dword v130, v[154:155], off
	global_load_dword v132, v[156:157], off
	global_load_dword v134, v[158:159], off
	global_load_dword v136, v[160:161], off
	s_add_u32 s8, s8, 0x24000
	s_addc_u32 s9, s9, 0
	v_lshl_add_u64 v[154:155], v[28:29], 0, s[8:9]
	s_add_u32 s100, s8, s13
	s_addc_u32 s101, s9, 0
	v_lshl_add_u64 v[156:157], v[28:29], 0, s[100:101]
	s_add_u32 s100, s8, s14
	s_addc_u32 s101, s9, 0
	v_lshl_add_u64 v[158:159], v[28:29], 0, s[100:101]
	s_add_u32 s100, s8, s15
	s_addc_u32 s101, s9, 0
	v_lshl_add_u64 v[160:161], v[28:29], 0, s[100:101]
	global_load_dword v138, v[154:155], off
	global_load_dword v140, v[156:157], off
	global_load_dword v142, v[158:159], off
	global_load_dword v144, v[160:161], off
	s_add_u32 s8, s8, 0x24000
	s_addc_u32 s9, s9, 0
.LBB0_302:
	v_lshl_add_u64 v[154:155], v[28:29], 0, s[8:9]
	s_add_u32 s100, s8, s13
	s_addc_u32 s101, s9, 0
	v_lshl_add_u64 v[156:157], v[28:29], 0, s[100:101]
	s_add_u32 s100, s8, s14
	s_addc_u32 s101, s9, 0
	v_lshl_add_u64 v[158:159], v[28:29], 0, s[100:101]
	s_add_u32 s100, s8, s15
	s_addc_u32 s101, s9, 0
	v_lshl_add_u64 v[160:161], v[28:29], 0, s[100:101]
	global_load_dword v146, v[154:155], off
	global_load_dword v148, v[156:157], off
	global_load_dword v150, v[158:159], off
	global_load_dword v152, v[160:161], off
	s_add_u32 s8, s8, 0x24000
	s_addc_u32 s9, s9, 0
	ds_read_b128 v[14:17], v49
	ds_read_b128 v[6:9], v49 offset:16
	ds_read_b128 v[10:13], v49 offset:32
	ds_read_b128 v[2:5], v49 offset:48
	ds_read2_b32 v[100:101], v49 offset0:16 offset1:36
	ds_read_b128 v[50:53], v49 offset:80
	ds_read_b128 v[54:57], v49 offset:96
	ds_read_b128 v[58:61], v49 offset:112
	ds_read_b128 v[62:65], v49 offset:128
	ds_read_b128 v[66:69], v49 offset:160
	ds_read_b128 v[70:73], v49 offset:176
	ds_read_b128 v[74:77], v49 offset:192
	ds_read_b128 v[78:81], v49 offset:208
	ds_read2_b32 v[102:103], v49 offset0:56 offset1:76
	ds_read_b128 v[82:85], v49 offset:240
	ds_read_b128 v[86:89], v49 offset:256
	ds_read_b128 v[90:93], v49 offset:272
	ds_read_b128 v[94:97], v49 offset:288
	s_waitcnt lgkmcnt(14)
	v_mov_b32_e32 v114, v11
	v_mov_b32_e32 v115, v12
	v_mov_b32_e32 v98, v15
	v_mov_b32_e32 v99, v16
	v_mov_b32_e32 v108, v7
	v_mov_b32_e32 v109, v8
	v_mov_b32_e32 v116, v3
	v_mov_b32_e32 v117, v4
	v_mov_b32_e32 v7, v17
	v_mov_b32_e32 v11, v9
	v_mov_b32_e32 v3, v13
	s_waitcnt lgkmcnt(13)
	v_mov_b32_e32 v4, v100
	s_waitcnt lgkmcnt(12)
	v_mov_b32_e32 v8, v51
	v_mov_b32_e32 v9, v52
	s_waitcnt lgkmcnt(11)
	v_mov_b32_e32 v12, v55
	v_mov_b32_e32 v13, v56
	s_waitcnt lgkmcnt(10)
	v_mov_b32_e32 v16, v59
	v_mov_b32_e32 v17, v60
	s_waitcnt lgkmcnt(9)
	v_mov_b32_e32 v118, v63
	v_mov_b32_e32 v119, v64
	v_mov_b32_e32 v55, v53
	v_mov_b32_e32 v59, v57
	v_mov_b32_e32 v63, v61
	v_mov_b32_e32 v64, v101
	s_waitcnt lgkmcnt(8)
	v_mov_b32_e32 v52, v67
	v_mov_b32_e32 v53, v68
	s_waitcnt lgkmcnt(7)
	v_mov_b32_e32 v56, v71
	v_mov_b32_e32 v57, v72
	s_waitcnt lgkmcnt(6)
	v_mov_b32_e32 v60, v75
	v_mov_b32_e32 v61, v76
	s_waitcnt lgkmcnt(5)
	v_mov_b32_e32 v100, v79
	v_mov_b32_e32 v101, v80
	v_mov_b32_e32 v71, v69
	v_mov_b32_e32 v75, v73
	v_mov_b32_e32 v79, v77
	s_waitcnt lgkmcnt(4)
	v_mov_b32_e32 v80, v102
	s_waitcnt lgkmcnt(3)
	v_mov_b32_e32 v68, v83
	v_mov_b32_e32 v69, v84
	s_waitcnt lgkmcnt(2)
	v_mov_b32_e32 v72, v87
	v_mov_b32_e32 v73, v88
	s_waitcnt lgkmcnt(0)
	v_mov_b32_e32 v77, v96
	v_mov_b32_e32 v96, v103
	v_mov_b32_e32 v102, v91
	v_mov_b32_e32 v103, v92
	v_mov_b32_e32 v76, v95
	v_mov_b32_e32 v87, v85
	v_mov_b32_e32 v91, v89
	v_mov_b32_e32 v95, v93
	v_add_u32_e32 v49, 0x140, v49
	s_waitcnt vmcnt(15)
; #define LAS __attribute__((address_space(3)))
; DI void phase_prep(const Params& p, LAS unsigned char* lds) {
;     ...
;       for (int k = 0; k < 128; ++k) { const float wv = wp[(size_t)k * NMODW]; const LAS float* sp = sc + (ks * 128 + k) * 20;
;         const f32x4 s0 = *(const LAS f32x4*)sp, s1 = *(const LAS f32x4*)(sp + 4), s2 = *(const LAS f32x4*)(sp + 8), s3 = *(const LAS f32x4*)(sp + 12); const float s16 = sp[16];
; #pragma unroll
;         for (int e = 0; e < 4; ++e) { a[e] += s0[e] * wv; a[4 + e] += s1[e] * wv; a[8 + e] += s2[e] * wv; a[12 + e] += s3[e] * wv; }
;         a[16] += s16 * wv; }
	v_fmac_f32_e32 v48, v104, v14
	v_pk_fma_f32 v[14:15], v[104:105], v[98:99], v[44:45] op_sel_hi:[0,1,1]
	v_pk_fma_f32 v[40:41], v[104:105], v[108:109], v[40:41] op_sel_hi:[0,1,1]
	v_pk_fma_f32 v[36:37], v[104:105], v[114:115], v[36:37] op_sel_hi:[0,1,1]
	v_pk_fma_f32 v[32:33], v[104:105], v[116:117], v[32:33] op_sel_hi:[0,1,1]
	v_pk_fma_f32 v[6:7], v[104:105], v[6:7], v[42:43] op_sel_hi:[0,1,1]
	v_pk_fma_f32 v[10:11], v[104:105], v[10:11], v[38:39] op_sel_hi:[0,1,1]
	v_pk_fma_f32 v[2:3], v[104:105], v[2:3], v[34:35] op_sel_hi:[0,1,1]
	v_pk_fma_f32 v[4:5], v[104:105], v[4:5], v[30:31] op_sel_hi:[0,1,1]
	s_waitcnt vmcnt(14)
	v_fmac_f32_e32 v48, v106, v50
	v_pk_fma_f32 v[8:9], v[106:107], v[8:9], v[14:15] op_sel_hi:[0,1,1]
	v_pk_fma_f32 v[12:13], v[106:107], v[12:13], v[40:41] op_sel_hi:[0,1,1]
	v_pk_fma_f32 v[14:15], v[106:107], v[16:17], v[36:37] op_sel_hi:[0,1,1]
	v_pk_fma_f32 v[16:17], v[106:107], v[118:119], v[32:33] op_sel_hi:[0,1,1]
	v_pk_fma_f32 v[6:7], v[106:107], v[54:55], v[6:7] op_sel_hi:[0,1,1]
	v_pk_fma_f32 v[10:11], v[106:107], v[58:59], v[10:11] op_sel_hi:[0,1,1]
	v_pk_fma_f32 v[2:3], v[106:107], v[62:63], v[2:3] op_sel_hi:[0,1,1]
	v_pk_fma_f32 v[4:5], v[106:107], v[64:65], v[4:5] op_sel_hi:[0,1,1]
	s_waitcnt vmcnt(13)
	v_fmac_f32_e32 v48, v110, v66
	v_pk_fma_f32 v[8:9], v[110:111], v[52:53], v[8:9] op_sel_hi:[0,1,1]
	v_pk_fma_f32 v[12:13], v[110:111], v[56:57], v[12:13] op_sel_hi:[0,1,1]
	v_pk_fma_f32 v[14:15], v[110:111], v[60:61], v[14:15] op_sel_hi:[0,1,1]
	v_pk_fma_f32 v[16:17], v[110:111], v[100:101], v[16:17] op_sel_hi:[0,1,1]
	v_pk_fma_f32 v[6:7], v[110:111], v[70:71], v[6:7] op_sel_hi:[0,1,1]
	v_pk_fma_f32 v[10:11], v[110:111], v[74:75], v[10:11] op_sel_hi:[0,1,1]
	v_pk_fma_f32 v[2:3], v[110:111], v[78:79], v[2:3] op_sel_hi:[0,1,1]
	v_pk_fma_f32 v[4:5], v[110:111], v[80:81], v[4:5] op_sel_hi:[0,1,1]
	s_waitcnt vmcnt(12)
	v_fmac_f32_e32 v48, v112, v82
	v_pk_fma_f32 v[44:45], v[112:113], v[68:69], v[8:9] op_sel_hi:[0,1,1]
	v_pk_fma_f32 v[40:41], v[112:113], v[72:73], v[12:13] op_sel_hi:[0,1,1]
	v_pk_fma_f32 v[36:37], v[112:113], v[102:103], v[14:15] op_sel_hi:[0,1,1]
	v_pk_fma_f32 v[32:33], v[112:113], v[76:77], v[16:17] op_sel_hi:[0,1,1]
	v_pk_fma_f32 v[42:43], v[112:113], v[86:87], v[6:7] op_sel_hi:[0,1,1]
	v_pk_fma_f32 v[38:39], v[112:113], v[90:91], v[10:11] op_sel_hi:[0,1,1]
	v_pk_fma_f32 v[34:35], v[112:113], v[94:95], v[2:3] op_sel_hi:[0,1,1]
	v_pk_fma_f32 v[30:31], v[112:113], v[96:97], v[4:5] op_sel_hi:[0,1,1]
	v_lshl_add_u64 v[154:155], v[28:29], 0, s[8:9]
	s_add_u32 s100, s8, s13
	s_addc_u32 s101, s9, 0
	v_lshl_add_u64 v[156:157], v[28:29], 0, s[100:101]
	s_add_u32 s100, s8, s14
	s_addc_u32 s101, s9, 0
	v_lshl_add_u64 v[158:159], v[28:29], 0, s[100:101]
	s_add_u32 s100, s8, s15
	s_addc_u32 s101, s9, 0
	v_lshl_add_u64 v[160:161], v[28:29], 0, s[100:101]
	global_load_dword v104, v[154:155], off
	global_load_dword v106, v[156:157], off
	global_load_dword v110, v[158:159], off
	global_load_dword v112, v[160:161], off
	s_add_u32 s8, s8, 0x24000
	s_addc_u32 s9, s9, 0
	ds_read_b128 v[14:17], v49
	ds_read_b128 v[6:9], v49 offset:16
	ds_read_b128 v[10:13], v49 offset:32
	ds_read_b128 v[2:5], v49 offset:48
	ds_read2_b32 v[100:101], v49 offset0:16 offset1:36
	ds_read_b128 v[50:53], v49 offset:80
	ds_read_b128 v[54:57], v49 offset:96
	ds_read_b128 v[58:61], v49 offset:112
	ds_read_b128 v[62:65], v49 offset:128
	ds_read_b128 v[66:69], v49 offset:160
	ds_read_b128 v[70:73], v49 offset:176
	ds_read_b128 v[74:77], v49 offset:192
	ds_read_b128 v[78:81], v49 offset:208
	ds_read2_b32 v[102:103], v49 offset0:56 offset1:76
	ds_read_b128 v[82:85], v49 offset:240
	ds_read_b128 v[86:89], v49 offset:256
	ds_read_b128 v[90:93], v49 offset:272
	ds_read_b128 v[94:97], v49 offset:288
	s_waitcnt lgkmcnt(14)
	v_mov_b32_e32 v114, v11
	v_mov_b32_e32 v115, v12
	v_mov_b32_e32 v98, v15
	v_mov_b32_e32 v99, v16
	v_mov_b32_e32 v108, v7
	v_mov_b32_e32 v109, v8
	v_mov_b32_e32 v116, v3
	v_mov_b32_e32 v117, v4
	v_mov_b32_e32 v7, v17
	v_mov_b32_e32 v11, v9
	v_mov_b32_e32 v3, v13
	s_waitcnt lgkmcnt(13)
	v_mov_b32_e32 v4, v100
	s_waitcnt lgkmcnt(12)
	v_mov_b32_e32 v8, v51
	v_mov_b32_e32 v9, v52
	s_waitcnt lgkmcnt(11)
	v_mov_b32_e32 v12, v55
	v_mov_b32_e32 v13, v56
	s_waitcnt lgkmcnt(10)
	v_mov_b32_e32 v16, v59
	v_mov_b32_e32 v17, v60
	s_waitcnt lgkmcnt(9)
	v_mov_b32_e32 v118, v63
	v_mov_b32_e32 v119, v64
	v_mov_b32_e32 v55, v53
	v_mov_b32_e32 v59, v57
	v_mov_b32_e32 v63, v61
	v_mov_b32_e32 v64, v101
	s_waitcnt lgkmcnt(8)
	v_mov_b32_e32 v52, v67
	v_mov_b32_e32 v53, v68
	s_waitcnt lgkmcnt(7)
	v_mov_b32_e32 v56, v71
	v_mov_b32_e32 v57, v72
	s_waitcnt lgkmcnt(6)
	v_mov_b32_e32 v60, v75
	v_mov_b32_e32 v61, v76
	s_waitcnt lgkmcnt(5)
	v_mov_b32_e32 v100, v79
	v_mov_b32_e32 v101, v80
	v_mov_b32_e32 v71, v69
	v_mov_b32_e32 v75, v73
	v_mov_b32_e32 v79, v77
	s_waitcnt lgkmcnt(4)
	v_mov_b32_e32 v80, v102
	s_waitcnt lgkmcnt(3)
	v_mov_b32_e32 v68, v83
	v_mov_b32_e32 v69, v84
	s_waitcnt lgkmcnt(2)
	v_mov_b32_e32 v72, v87
	v_mov_b32_e32 v73, v88
	s_waitcnt lgkmcnt(0)
	v_mov_b32_e32 v77, v96
	v_mov_b32_e32 v96, v103
	v_mov_b32_e32 v102, v91
	v_mov_b32_e32 v103, v92
	v_mov_b32_e32 v76, v95
	v_mov_b32_e32 v87, v85
	v_mov_b32_e32 v91, v89
	v_mov_b32_e32 v95, v93
	v_add_u32_e32 v49, 0x140, v49
	s_waitcnt vmcnt(15)
	v_fmac_f32_e32 v48, v130, v14
	v_pk_fma_f32 v[14:15], v[130:131], v[98:99], v[44:45] op_sel_hi:[0,1,1]
	v_pk_fma_f32 v[40:41], v[130:131], v[108:109], v[40:41] op_sel_hi:[0,1,1]
	v_pk_fma_f32 v[36:37], v[130:131], v[114:115], v[36:37] op_sel_hi:[0,1,1]
	v_pk_fma_f32 v[32:33], v[130:131], v[116:117], v[32:33] op_sel_hi:[0,1,1]
	v_pk_fma_f32 v[6:7], v[130:131], v[6:7], v[42:43] op_sel_hi:[0,1,1]
	v_pk_fma_f32 v[10:11], v[130:131], v[10:11], v[38:39] op_sel_hi:[0,1,1]
	v_pk_fma_f32 v[2:3], v[130:131], v[2:3], v[34:35] op_sel_hi:[0,1,1]
	v_pk_fma_f32 v[4:5], v[130:131], v[4:5], v[30:31] op_sel_hi:[0,1,1]
	s_waitcnt vmcnt(14)
; #define LAS __attribute__((address_space(3)))
; DI void phase_prep(const Params& p, LAS unsigned char* lds) {
;     ...
;       for (int k = 0; k < 128; ++k) { const float wv = wp[(size_t)k * NMODW]; const LAS float* sp = sc + (ks * 128 + k) * 20;
;         const f32x4 s0 = *(const LAS f32x4*)sp, s1 = *(const LAS f32x4*)(sp + 4), s2 = *(const LAS f32x4*)(sp + 8), s3 = *(const LAS f32x4*)(sp + 12); const float s16 = sp[16];
; #pragma unroll
;         for (int e = 0; e < 4; ++e) { a[e] += s0[e] * wv; a[4 + e] += s1[e] * wv; a[8 + e] += s2[e] * wv; a[12 + e] += s3[e] * wv; }
;         a[16] += s16 * wv; }
	v_fmac_f32_e32 v48, v132, v50
	v_pk_fma_f32 v[8:9], v[132:133], v[8:9], v[14:15] op_sel_hi:[0,1,1]
	v_pk_fma_f32 v[12:13], v[132:133], v[12:13], v[40:41] op_sel_hi:[0,1,1]
	v_pk_fma_f32 v[14:15], v[132:133], v[16:17], v[36:37] op_sel_hi:[0,1,1]
	v_pk_fma_f32 v[16:17], v[132:133], v[118:119], v[32:33] op_sel_hi:[0,1,1]
	v_pk_fma_f32 v[6:7], v[132:133], v[54:55], v[6:7] op_sel_hi:[0,1,1]
	v_pk_fma_f32 v[10:11], v[132:133], v[58:59], v[10:11] op_sel_hi:[0,1,1]
	v_pk_fma_f32 v[2:3], v[132:133], v[62:63], v[2:3] op_sel_hi:[0,1,1]
	v_pk_fma_f32 v[4:5], v[132:133], v[64:65], v[4:5] op_sel_hi:[0,1,1]
	s_waitcnt vmcnt(13)
	v_fmac_f32_e32 v48, v134, v66
	v_pk_fma_f32 v[8:9], v[134:135], v[52:53], v[8:9] op_sel_hi:[0,1,1]
	v_pk_fma_f32 v[12:13], v[134:135], v[56:57], v[12:13] op_sel_hi:[0,1,1]
	v_pk_fma_f32 v[14:15], v[134:135], v[60:61], v[14:15] op_sel_hi:[0,1,1]
	v_pk_fma_f32 v[16:17], v[134:135], v[100:101], v[16:17] op_sel_hi:[0,1,1]
	v_pk_fma_f32 v[6:7], v[134:135], v[70:71], v[6:7] op_sel_hi:[0,1,1]
	v_pk_fma_f32 v[10:11], v[134:135], v[74:75], v[10:11] op_sel_hi:[0,1,1]
	v_pk_fma_f32 v[2:3], v[134:135], v[78:79], v[2:3] op_sel_hi:[0,1,1]
	v_pk_fma_f32 v[4:5], v[134:135], v[80:81], v[4:5] op_sel_hi:[0,1,1]
	s_waitcnt vmcnt(12)
	v_fmac_f32_e32 v48, v136, v82
	v_pk_fma_f32 v[44:45], v[136:137], v[68:69], v[8:9] op_sel_hi:[0,1,1]
	v_pk_fma_f32 v[40:41], v[136:137], v[72:73], v[12:13] op_sel_hi:[0,1,1]
	v_pk_fma_f32 v[36:37], v[136:137], v[102:103], v[14:15] op_sel_hi:[0,1,1]
	v_pk_fma_f32 v[32:33], v[136:137], v[76:77], v[16:17] op_sel_hi:[0,1,1]
	v_pk_fma_f32 v[42:43], v[136:137], v[86:87], v[6:7] op_sel_hi:[0,1,1]
	v_pk_fma_f32 v[38:39], v[136:137], v[90:91], v[10:11] op_sel_hi:[0,1,1]
	v_pk_fma_f32 v[34:35], v[136:137], v[94:95], v[2:3] op_sel_hi:[0,1,1]
	v_pk_fma_f32 v[30:31], v[136:137], v[96:97], v[4:5] op_sel_hi:[0,1,1]
	v_lshl_add_u64 v[154:155], v[28:29], 0, s[8:9]
	s_add_u32 s100, s8, s13
	s_addc_u32 s101, s9, 0
	v_lshl_add_u64 v[156:157], v[28:29], 0, s[100:101]
	s_add_u32 s100, s8, s14
	s_addc_u32 s101, s9, 0
	v_lshl_add_u64 v[158:159], v[28:29], 0, s[100:101]
	s_add_u32 s100, s8, s15
	s_addc_u32 s101, s9, 0
	v_lshl_add_u64 v[160:161], v[28:29], 0, s[100:101]
	global_load_dword v130, v[154:155], off
	global_load_dword v132, v[156:157], off
	global_load_dword v134, v[158:159], off
	global_load_dword v136, v[160:161], off
	s_add_u32 s8, s8, 0x24000
	s_addc_u32 s9, s9, 0
	ds_read_b128 v[14:17], v49
	ds_read_b128 v[6:9], v49 offset:16
	ds_read_b128 v[10:13], v49 offset:32
	ds_read_b128 v[2:5], v49 offset:48
	ds_read2_b32 v[100:101], v49 offset0:16 offset1:36
	ds_read_b128 v[50:53], v49 offset:80
	ds_read_b128 v[54:57], v49 offset:96
	ds_read_b128 v[58:61], v49 offset:112
	ds_read_b128 v[62:65], v49 offset:128
	ds_read_b128 v[66:69], v49 offset:160
	ds_read_b128 v[70:73], v49 offset:176
	ds_read_b128 v[74:77], v49 offset:192
	ds_read_b128 v[78:81], v49 offset:208
	ds_read2_b32 v[102:103], v49 offset0:56 offset1:76
	ds_read_b128 v[82:85], v49 offset:240
	ds_read_b128 v[86:89], v49 offset:256
	ds_read_b128 v[90:93], v49 offset:272
	ds_read_b128 v[94:97], v49 offset:288
	s_waitcnt lgkmcnt(14)
	v_mov_b32_e32 v114, v11
	v_mov_b32_e32 v115, v12
	v_mov_b32_e32 v98, v15
	v_mov_b32_e32 v99, v16
	v_mov_b32_e32 v108, v7
	v_mov_b32_e32 v109, v8
	v_mov_b32_e32 v116, v3
	v_mov_b32_e32 v117, v4
	v_mov_b32_e32 v7, v17
	v_mov_b32_e32 v11, v9
	v_mov_b32_e32 v3, v13
	s_waitcnt lgkmcnt(13)
	v_mov_b32_e32 v4, v100
	s_waitcnt lgkmcnt(12)
	v_mov_b32_e32 v8, v51
	v_mov_b32_e32 v9, v52
	s_waitcnt lgkmcnt(11)
	v_mov_b32_e32 v12, v55
	v_mov_b32_e32 v13, v56
	s_waitcnt lgkmcnt(10)
	v_mov_b32_e32 v16, v59
	v_mov_b32_e32 v17, v60
	s_waitcnt lgkmcnt(9)
	v_mov_b32_e32 v118, v63
	v_mov_b32_e32 v119, v64
	v_mov_b32_e32 v55, v53
	v_mov_b32_e32 v59, v57
	v_mov_b32_e32 v63, v61
	v_mov_b32_e32 v64, v101
	s_waitcnt lgkmcnt(8)
	v_mov_b32_e32 v52, v67
	v_mov_b32_e32 v53, v68
	s_waitcnt lgkmcnt(7)
	v_mov_b32_e32 v56, v71
	v_mov_b32_e32 v57, v72
	s_waitcnt lgkmcnt(6)
	v_mov_b32_e32 v60, v75
	v_mov_b32_e32 v61, v76
	s_waitcnt lgkmcnt(5)
	v_mov_b32_e32 v100, v79
	v_mov_b32_e32 v101, v80
	v_mov_b32_e32 v71, v69
	v_mov_b32_e32 v75, v73
	v_mov_b32_e32 v79, v77
	s_waitcnt lgkmcnt(4)
	v_mov_b32_e32 v80, v102
	s_waitcnt lgkmcnt(3)
	v_mov_b32_e32 v68, v83
	v_mov_b32_e32 v69, v84
	s_waitcnt lgkmcnt(2)
	v_mov_b32_e32 v72, v87
	v_mov_b32_e32 v73, v88
	s_waitcnt lgkmcnt(0)
	v_mov_b32_e32 v77, v96
	v_mov_b32_e32 v96, v103
	v_mov_b32_e32 v102, v91
	v_mov_b32_e32 v103, v92
	v_mov_b32_e32 v76, v95
	v_mov_b32_e32 v87, v85
	v_mov_b32_e32 v91, v89
	v_mov_b32_e32 v95, v93
	v_add_u32_e32 v49, 0x140, v49
	s_waitcnt vmcnt(15)
	v_fmac_f32_e32 v48, v138, v14
	v_pk_fma_f32 v[14:15], v[138:139], v[98:99], v[44:45] op_sel_hi:[0,1,1]
	v_pk_fma_f32 v[40:41], v[138:139], v[108:109], v[40:41] op_sel_hi:[0,1,1]
	v_pk_fma_f32 v[36:37], v[138:139], v[114:115], v[36:37] op_sel_hi:[0,1,1]
	v_pk_fma_f32 v[32:33], v[138:139], v[116:117], v[32:33] op_sel_hi:[0,1,1]
	v_pk_fma_f32 v[6:7], v[138:139], v[6:7], v[42:43] op_sel_hi:[0,1,1]
	v_pk_fma_f32 v[10:11], v[138:139], v[10:11], v[38:39] op_sel_hi:[0,1,1]
	v_pk_fma_f32 v[2:3], v[138:139], v[2:3], v[34:35] op_sel_hi:[0,1,1]
	v_pk_fma_f32 v[4:5], v[138:139], v[4:5], v[30:31] op_sel_hi:[0,1,1]
	s_waitcnt vmcnt(14)
	v_fmac_f32_e32 v48, v140, v50
	v_pk_fma_f32 v[8:9], v[140:141], v[8:9], v[14:15] op_sel_hi:[0,1,1]
	v_pk_fma_f32 v[12:13], v[140:141], v[12:13], v[40:41] op_sel_hi:[0,1,1]
	v_pk_fma_f32 v[14:15], v[140:141], v[16:17], v[36:37] op_sel_hi:[0,1,1]
	v_pk_fma_f32 v[16:17], v[140:141], v[118:119], v[32:33] op_sel_hi:[0,1,1]
	v_pk_fma_f32 v[6:7], v[140:141], v[54:55], v[6:7] op_sel_hi:[0,1,1]
	v_pk_fma_f32 v[10:11], v[140:141], v[58:59], v[10:11] op_sel_hi:[0,1,1]
	v_pk_fma_f32 v[2:3], v[140:141], v[62:63], v[2:3] op_sel_hi:[0,1,1]
	v_pk_fma_f32 v[4:5], v[140:141], v[64:65], v[4:5] op_sel_hi:[0,1,1]
	s_waitcnt vmcnt(13)
; #define LAS __attribute__((address_space(3)))
; DI void phase_prep(const Params& p, LAS unsigned char* lds) {
;     ...
;       for (int k = 0; k < 128; ++k) { const float wv = wp[(size_t)k * NMODW]; const LAS float* sp = sc + (ks * 128 + k) * 20;
;         const f32x4 s0 = *(const LAS f32x4*)sp, s1 = *(const LAS f32x4*)(sp + 4), s2 = *(const LAS f32x4*)(sp + 8), s3 = *(const LAS f32x4*)(sp + 12); const float s16 = sp[16];
; #pragma unroll
;         for (int e = 0; e < 4; ++e) { a[e] += s0[e] * wv; a[4 + e] += s1[e] * wv; a[8 + e] += s2[e] * wv; a[12 + e] += s3[e] * wv; }
;         a[16] += s16 * wv; }
	v_fmac_f32_e32 v48, v142, v66
	v_pk_fma_f32 v[8:9], v[142:143], v[52:53], v[8:9] op_sel_hi:[0,1,1]
	v_pk_fma_f32 v[12:13], v[142:143], v[56:57], v[12:13] op_sel_hi:[0,1,1]
	v_pk_fma_f32 v[14:15], v[142:143], v[60:61], v[14:15] op_sel_hi:[0,1,1]
	v_pk_fma_f32 v[16:17], v[142:143], v[100:101], v[16:17] op_sel_hi:[0,1,1]
	v_pk_fma_f32 v[6:7], v[142:143], v[70:71], v[6:7] op_sel_hi:[0,1,1]
	v_pk_fma_f32 v[10:11], v[142:143], v[74:75], v[10:11] op_sel_hi:[0,1,1]
	v_pk_fma_f32 v[2:3], v[142:143], v[78:79], v[2:3] op_sel_hi:[0,1,1]
	v_pk_fma_f32 v[4:5], v[142:143], v[80:81], v[4:5] op_sel_hi:[0,1,1]
	s_waitcnt vmcnt(12)
	v_fmac_f32_e32 v48, v144, v82
	v_pk_fma_f32 v[44:45], v[144:145], v[68:69], v[8:9] op_sel_hi:[0,1,1]
	v_pk_fma_f32 v[40:41], v[144:145], v[72:73], v[12:13] op_sel_hi:[0,1,1]
	v_pk_fma_f32 v[36:37], v[144:145], v[102:103], v[14:15] op_sel_hi:[0,1,1]
	v_pk_fma_f32 v[32:33], v[144:145], v[76:77], v[16:17] op_sel_hi:[0,1,1]
	v_pk_fma_f32 v[42:43], v[144:145], v[86:87], v[6:7] op_sel_hi:[0,1,1]
	v_pk_fma_f32 v[38:39], v[144:145], v[90:91], v[10:11] op_sel_hi:[0,1,1]
	v_pk_fma_f32 v[34:35], v[144:145], v[94:95], v[2:3] op_sel_hi:[0,1,1]
	v_pk_fma_f32 v[30:31], v[144:145], v[96:97], v[4:5] op_sel_hi:[0,1,1]
	v_lshl_add_u64 v[154:155], v[28:29], 0, s[8:9]
	s_add_u32 s100, s8, s13
	s_addc_u32 s101, s9, 0
	v_lshl_add_u64 v[156:157], v[28:29], 0, s[100:101]
	s_add_u32 s100, s8, s14
	s_addc_u32 s101, s9, 0
	v_lshl_add_u64 v[158:159], v[28:29], 0, s[100:101]
	s_add_u32 s100, s8, s15
	s_addc_u32 s101, s9, 0
	v_lshl_add_u64 v[160:161], v[28:29], 0, s[100:101]
	global_load_dword v138, v[154:155], off
	global_load_dword v140, v[156:157], off
	global_load_dword v142, v[158:159], off
	global_load_dword v144, v[160:161], off
	s_add_u32 s8, s8, 0x24000
	s_addc_u32 s9, s9, 0
	ds_read_b128 v[14:17], v49
	ds_read_b128 v[6:9], v49 offset:16
	ds_read_b128 v[10:13], v49 offset:32
	ds_read_b128 v[2:5], v49 offset:48
	ds_read2_b32 v[100:101], v49 offset0:16 offset1:36
	ds_read_b128 v[50:53], v49 offset:80
	ds_read_b128 v[54:57], v49 offset:96
	ds_read_b128 v[58:61], v49 offset:112
	ds_read_b128 v[62:65], v49 offset:128
	ds_read_b128 v[66:69], v49 offset:160
	ds_read_b128 v[70:73], v49 offset:176
	ds_read_b128 v[74:77], v49 offset:192
	ds_read_b128 v[78:81], v49 offset:208
	ds_read2_b32 v[102:103], v49 offset0:56 offset1:76
	ds_read_b128 v[82:85], v49 offset:240
	ds_read_b128 v[86:89], v49 offset:256
	ds_read_b128 v[90:93], v49 offset:272
	ds_read_b128 v[94:97], v49 offset:288
	s_waitcnt lgkmcnt(14)
	v_mov_b32_e32 v114, v11
	v_mov_b32_e32 v115, v12
	v_mov_b32_e32 v98, v15
	v_mov_b32_e32 v99, v16
	v_mov_b32_e32 v108, v7
	v_mov_b32_e32 v109, v8
	v_mov_b32_e32 v116, v3
	v_mov_b32_e32 v117, v4
	v_mov_b32_e32 v7, v17
	v_mov_b32_e32 v11, v9
	v_mov_b32_e32 v3, v13
	s_waitcnt lgkmcnt(13)
	v_mov_b32_e32 v4, v100
	s_waitcnt lgkmcnt(12)
	v_mov_b32_e32 v8, v51
	v_mov_b32_e32 v9, v52
	s_waitcnt lgkmcnt(11)
	v_mov_b32_e32 v12, v55
	v_mov_b32_e32 v13, v56
	s_waitcnt lgkmcnt(10)
	v_mov_b32_e32 v16, v59
	v_mov_b32_e32 v17, v60
	s_waitcnt lgkmcnt(9)
	v_mov_b32_e32 v118, v63
	v_mov_b32_e32 v119, v64
	v_mov_b32_e32 v55, v53
	v_mov_b32_e32 v59, v57
	v_mov_b32_e32 v63, v61
	v_mov_b32_e32 v64, v101
	s_waitcnt lgkmcnt(8)
	v_mov_b32_e32 v52, v67
	v_mov_b32_e32 v53, v68
	s_waitcnt lgkmcnt(7)
	v_mov_b32_e32 v56, v71
	v_mov_b32_e32 v57, v72
	s_waitcnt lgkmcnt(6)
	v_mov_b32_e32 v60, v75
	v_mov_b32_e32 v61, v76
	s_waitcnt lgkmcnt(5)
	v_mov_b32_e32 v100, v79
	v_mov_b32_e32 v101, v80
	v_mov_b32_e32 v71, v69
	v_mov_b32_e32 v75, v73
	v_mov_b32_e32 v79, v77
	s_waitcnt lgkmcnt(4)
	v_mov_b32_e32 v80, v102
	s_waitcnt lgkmcnt(3)
	v_mov_b32_e32 v68, v83
	v_mov_b32_e32 v69, v84
	s_waitcnt lgkmcnt(2)
	v_mov_b32_e32 v72, v87
	v_mov_b32_e32 v73, v88
	s_waitcnt lgkmcnt(0)
	v_mov_b32_e32 v77, v96
	v_mov_b32_e32 v96, v103
	v_mov_b32_e32 v102, v91
	v_mov_b32_e32 v103, v92
	v_mov_b32_e32 v76, v95
	v_mov_b32_e32 v87, v85
	v_mov_b32_e32 v91, v89
	v_mov_b32_e32 v95, v93
	v_add_u32_e32 v49, 0x140, v49
	s_waitcnt vmcnt(15)
	v_fmac_f32_e32 v48, v146, v14
	v_pk_fma_f32 v[14:15], v[146:147], v[98:99], v[44:45] op_sel_hi:[0,1,1]
	v_pk_fma_f32 v[40:41], v[146:147], v[108:109], v[40:41] op_sel_hi:[0,1,1]
	v_pk_fma_f32 v[36:37], v[146:147], v[114:115], v[36:37] op_sel_hi:[0,1,1]
	v_pk_fma_f32 v[32:33], v[146:147], v[116:117], v[32:33] op_sel_hi:[0,1,1]
	v_pk_fma_f32 v[6:7], v[146:147], v[6:7], v[42:43] op_sel_hi:[0,1,1]
	v_pk_fma_f32 v[10:11], v[146:147], v[10:11], v[38:39] op_sel_hi:[0,1,1]
	v_pk_fma_f32 v[2:3], v[146:147], v[2:3], v[34:35] op_sel_hi:[0,1,1]
	v_pk_fma_f32 v[4:5], v[146:147], v[4:5], v[30:31] op_sel_hi:[0,1,1]
	s_waitcnt vmcnt(14)
	v_fmac_f32_e32 v48, v148, v50
	v_pk_fma_f32 v[8:9], v[148:149], v[8:9], v[14:15] op_sel_hi:[0,1,1]
	v_pk_fma_f32 v[12:13], v[148:149], v[12:13], v[40:41] op_sel_hi:[0,1,1]
	v_pk_fma_f32 v[14:15], v[148:149], v[16:17], v[36:37] op_sel_hi:[0,1,1]
	v_pk_fma_f32 v[16:17], v[148:149], v[118:119], v[32:33] op_sel_hi:[0,1,1]
	v_pk_fma_f32 v[6:7], v[148:149], v[54:55], v[6:7] op_sel_hi:[0,1,1]
	v_pk_fma_f32 v[10:11], v[148:149], v[58:59], v[10:11] op_sel_hi:[0,1,1]
	v_pk_fma_f32 v[2:3], v[148:149], v[62:63], v[2:3] op_sel_hi:[0,1,1]
	v_pk_fma_f32 v[4:5], v[148:149], v[64:65], v[4:5] op_sel_hi:[0,1,1]
	s_waitcnt vmcnt(13)
	v_fmac_f32_e32 v48, v150, v66
	v_pk_fma_f32 v[8:9], v[150:151], v[52:53], v[8:9] op_sel_hi:[0,1,1]
	v_pk_fma_f32 v[12:13], v[150:151], v[56:57], v[12:13] op_sel_hi:[0,1,1]
	v_pk_fma_f32 v[14:15], v[150:151], v[60:61], v[14:15] op_sel_hi:[0,1,1]
	v_pk_fma_f32 v[16:17], v[150:151], v[100:101], v[16:17] op_sel_hi:[0,1,1]
	v_pk_fma_f32 v[6:7], v[150:151], v[70:71], v[6:7] op_sel_hi:[0,1,1]
	v_pk_fma_f32 v[10:11], v[150:151], v[74:75], v[10:11] op_sel_hi:[0,1,1]
	v_pk_fma_f32 v[2:3], v[150:151], v[78:79], v[2:3] op_sel_hi:[0,1,1]
	v_pk_fma_f32 v[4:5], v[150:151], v[80:81], v[4:5] op_sel_hi:[0,1,1]
	s_waitcnt vmcnt(12)
	v_fmac_f32_e32 v48, v152, v82
	v_pk_fma_f32 v[44:45], v[152:153], v[68:69], v[8:9] op_sel_hi:[0,1,1]
	v_pk_fma_f32 v[40:41], v[152:153], v[72:73], v[12:13] op_sel_hi:[0,1,1]
	v_pk_fma_f32 v[36:37], v[152:153], v[102:103], v[14:15] op_sel_hi:[0,1,1]
	v_pk_fma_f32 v[32:33], v[152:153], v[76:77], v[16:17] op_sel_hi:[0,1,1]
	v_pk_fma_f32 v[42:43], v[152:153], v[86:87], v[6:7] op_sel_hi:[0,1,1]
	v_pk_fma_f32 v[38:39], v[152:153], v[90:91], v[10:11] op_sel_hi:[0,1,1]
	v_pk_fma_f32 v[34:35], v[152:153], v[94:95], v[2:3] op_sel_hi:[0,1,1]
	v_pk_fma_f32 v[30:31], v[152:153], v[96:97], v[4:5] op_sel_hi:[0,1,1]
	s_cmp_lg_u32 s8, 0x45c000
	s_cbranch_scc1 .LBB0_302
; #define LAS __attribute__((address_space(3)))
; DI void phase_prep(const Params& p, LAS unsigned char* lds) {
;     ...
;       for (int k = 0; k < 128; ++k) { const float wv = wp[(size_t)k * NMODW]; const LAS float* sp = sc + (ks * 128 + k) * 20;
;         const f32x4 s0 = *(const LAS f32x4*)sp, s1 = *(const LAS f32x4*)(sp + 4), s2 = *(const LAS f32x4*)(sp + 8), s3 = *(const LAS f32x4*)(sp + 12); const float s16 = sp[16];
; #pragma unroll
;         for (int e = 0; e < 4; ++e) { a[e] += s0[e] * wv; a[4 + e] += s1[e] * wv; a[8 + e] += s2[e] * wv; a[12 + e] += s3[e] * wv; }
;         a[16] += s16 * wv; }
	v_lshl_add_u64 v[154:155], v[28:29], 0, s[8:9]
	s_add_u32 s100, s8, s13
	s_addc_u32 s101, s9, 0
	v_lshl_add_u64 v[156:157], v[28:29], 0, s[100:101]
	s_add_u32 s100, s8, s14
	s_addc_u32 s101, s9, 0
	v_lshl_add_u64 v[158:159], v[28:29], 0, s[100:101]
	s_add_u32 s100, s8, s15
	s_addc_u32 s101, s9, 0
	v_lshl_add_u64 v[160:161], v[28:29], 0, s[100:101]
	global_load_dword v146, v[154:155], off
	global_load_dword v148, v[156:157], off
	global_load_dword v150, v[158:159], off
	global_load_dword v152, v[160:161], off
	s_add_u32 s8, s8, 0x24000
	s_addc_u32 s9, s9, 0
	ds_read_b128 v[14:17], v49
	ds_read_b128 v[6:9], v49 offset:16
	ds_read_b128 v[10:13], v49 offset:32
	ds_read_b128 v[2:5], v49 offset:48
	ds_read2_b32 v[100:101], v49 offset0:16 offset1:36
	ds_read_b128 v[50:53], v49 offset:80
	ds_read_b128 v[54:57], v49 offset:96
	ds_read_b128 v[58:61], v49 offset:112
	ds_read_b128 v[62:65], v49 offset:128
	ds_read_b128 v[66:69], v49 offset:160
	ds_read_b128 v[70:73], v49 offset:176
	ds_read_b128 v[74:77], v49 offset:192
	ds_read_b128 v[78:81], v49 offset:208
	ds_read2_b32 v[102:103], v49 offset0:56 offset1:76
	ds_read_b128 v[82:85], v49 offset:240
	ds_read_b128 v[86:89], v49 offset:256
	ds_read_b128 v[90:93], v49 offset:272
	ds_read_b128 v[94:97], v49 offset:288
	s_waitcnt lgkmcnt(14)
	v_mov_b32_e32 v114, v11
	v_mov_b32_e32 v115, v12
	v_mov_b32_e32 v98, v15
	v_mov_b32_e32 v99, v16
	v_mov_b32_e32 v108, v7
	v_mov_b32_e32 v109, v8
	v_mov_b32_e32 v116, v3
	v_mov_b32_e32 v117, v4
	v_mov_b32_e32 v7, v17
	v_mov_b32_e32 v11, v9
	v_mov_b32_e32 v3, v13
	s_waitcnt lgkmcnt(13)
	v_mov_b32_e32 v4, v100
	s_waitcnt lgkmcnt(12)
	v_mov_b32_e32 v8, v51
	v_mov_b32_e32 v9, v52
	s_waitcnt lgkmcnt(11)
	v_mov_b32_e32 v12, v55
	v_mov_b32_e32 v13, v56
	s_waitcnt lgkmcnt(10)
	v_mov_b32_e32 v16, v59
	v_mov_b32_e32 v17, v60
	s_waitcnt lgkmcnt(9)
	v_mov_b32_e32 v118, v63
	v_mov_b32_e32 v119, v64
	v_mov_b32_e32 v55, v53
	v_mov_b32_e32 v59, v57
	v_mov_b32_e32 v63, v61
	v_mov_b32_e32 v64, v101
	s_waitcnt lgkmcnt(8)
	v_mov_b32_e32 v52, v67
	v_mov_b32_e32 v53, v68
	s_waitcnt lgkmcnt(7)
	v_mov_b32_e32 v56, v71
	v_mov_b32_e32 v57, v72
	s_waitcnt lgkmcnt(6)
	v_mov_b32_e32 v60, v75
	v_mov_b32_e32 v61, v76
	s_waitcnt lgkmcnt(5)
	v_mov_b32_e32 v100, v79
	v_mov_b32_e32 v101, v80
	v_mov_b32_e32 v71, v69
	v_mov_b32_e32 v75, v73
	v_mov_b32_e32 v79, v77
	s_waitcnt lgkmcnt(4)
	v_mov_b32_e32 v80, v102
	s_waitcnt lgkmcnt(3)
	v_mov_b32_e32 v68, v83
	v_mov_b32_e32 v69, v84
	s_waitcnt lgkmcnt(2)
	v_mov_b32_e32 v72, v87
	v_mov_b32_e32 v73, v88
	s_waitcnt lgkmcnt(0)
	v_mov_b32_e32 v77, v96
	v_mov_b32_e32 v96, v103
	v_mov_b32_e32 v102, v91
	v_mov_b32_e32 v103, v92
	v_mov_b32_e32 v76, v95
	v_mov_b32_e32 v87, v85
	v_mov_b32_e32 v91, v89
	v_mov_b32_e32 v95, v93
	v_add_u32_e32 v49, 0x140, v49
	s_waitcnt vmcnt(15)
	v_fmac_f32_e32 v48, v104, v14
	v_pk_fma_f32 v[14:15], v[104:105], v[98:99], v[44:45] op_sel_hi:[0,1,1]
	v_pk_fma_f32 v[40:41], v[104:105], v[108:109], v[40:41] op_sel_hi:[0,1,1]
	v_pk_fma_f32 v[36:37], v[104:105], v[114:115], v[36:37] op_sel_hi:[0,1,1]
	v_pk_fma_f32 v[32:33], v[104:105], v[116:117], v[32:33] op_sel_hi:[0,1,1]
	v_pk_fma_f32 v[6:7], v[104:105], v[6:7], v[42:43] op_sel_hi:[0,1,1]
	v_pk_fma_f32 v[10:11], v[104:105], v[10:11], v[38:39] op_sel_hi:[0,1,1]
	v_pk_fma_f32 v[2:3], v[104:105], v[2:3], v[34:35] op_sel_hi:[0,1,1]
	v_pk_fma_f32 v[4:5], v[104:105], v[4:5], v[30:31] op_sel_hi:[0,1,1]
	s_waitcnt vmcnt(14)
	v_fmac_f32_e32 v48, v106, v50
	v_pk_fma_f32 v[8:9], v[106:107], v[8:9], v[14:15] op_sel_hi:[0,1,1]
	v_pk_fma_f32 v[12:13], v[106:107], v[12:13], v[40:41] op_sel_hi:[0,1,1]
	v_pk_fma_f32 v[14:15], v[106:107], v[16:17], v[36:37] op_sel_hi:[0,1,1]
	v_pk_fma_f32 v[16:17], v[106:107], v[118:119], v[32:33] op_sel_hi:[0,1,1]
	v_pk_fma_f32 v[6:7], v[106:107], v[54:55], v[6:7] op_sel_hi:[0,1,1]
	v_pk_fma_f32 v[10:11], v[106:107], v[58:59], v[10:11] op_sel_hi:[0,1,1]
	v_pk_fma_f32 v[2:3], v[106:107], v[62:63], v[2:3] op_sel_hi:[0,1,1]
	v_pk_fma_f32 v[4:5], v[106:107], v[64:65], v[4:5] op_sel_hi:[0,1,1]
	s_waitcnt vmcnt(13)
	v_fmac_f32_e32 v48, v110, v66
	v_pk_fma_f32 v[8:9], v[110:111], v[52:53], v[8:9] op_sel_hi:[0,1,1]
	v_pk_fma_f32 v[12:13], v[110:111], v[56:57], v[12:13] op_sel_hi:[0,1,1]
	v_pk_fma_f32 v[14:15], v[110:111], v[60:61], v[14:15] op_sel_hi:[0,1,1]
	v_pk_fma_f32 v[16:17], v[110:111], v[100:101], v[16:17] op_sel_hi:[0,1,1]
	v_pk_fma_f32 v[6:7], v[110:111], v[70:71], v[6:7] op_sel_hi:[0,1,1]
	v_pk_fma_f32 v[10:11], v[110:111], v[74:75], v[10:11] op_sel_hi:[0,1,1]
	v_pk_fma_f32 v[2:3], v[110:111], v[78:79], v[2:3] op_sel_hi:[0,1,1]
	v_pk_fma_f32 v[4:5], v[110:111], v[80:81], v[4:5] op_sel_hi:[0,1,1]
	s_waitcnt vmcnt(12)
	v_fmac_f32_e32 v48, v112, v82
	v_pk_fma_f32 v[44:45], v[112:113], v[68:69], v[8:9] op_sel_hi:[0,1,1]
	v_pk_fma_f32 v[40:41], v[112:113], v[72:73], v[12:13] op_sel_hi:[0,1,1]
	v_pk_fma_f32 v[36:37], v[112:113], v[102:103], v[14:15] op_sel_hi:[0,1,1]
	v_pk_fma_f32 v[32:33], v[112:113], v[76:77], v[16:17] op_sel_hi:[0,1,1]
	v_pk_fma_f32 v[42:43], v[112:113], v[86:87], v[6:7] op_sel_hi:[0,1,1]
	v_pk_fma_f32 v[38:39], v[112:113], v[90:91], v[10:11] op_sel_hi:[0,1,1]
	v_pk_fma_f32 v[34:35], v[112:113], v[94:95], v[2:3] op_sel_hi:[0,1,1]
	v_pk_fma_f32 v[30:31], v[112:113], v[96:97], v[4:5] op_sel_hi:[0,1,1]
	ds_read_b128 v[14:17], v49
	ds_read_b128 v[6:9], v49 offset:16
	ds_read_b128 v[10:13], v49 offset:32
	ds_read_b128 v[2:5], v49 offset:48
	ds_read2_b32 v[100:101], v49 offset0:16 offset1:36
	ds_read_b128 v[50:53], v49 offset:80
	ds_read_b128 v[54:57], v49 offset:96
	ds_read_b128 v[58:61], v49 offset:112
	ds_read_b128 v[62:65], v49 offset:128
	ds_read_b128 v[66:69], v49 offset:160
	ds_read_b128 v[70:73], v49 offset:176
	ds_read_b128 v[74:77], v49 offset:192
	ds_read_b128 v[78:81], v49 offset:208
	ds_read2_b32 v[102:103], v49 offset0:56 offset1:76
	ds_read_b128 v[82:85], v49 offset:240
	ds_read_b128 v[86:89], v49 offset:256
	ds_read_b128 v[90:93], v49 offset:272
	ds_read_b128 v[94:97], v49 offset:288
	s_waitcnt lgkmcnt(14)
; #define LAS __attribute__((address_space(3)))
; DI void phase_prep(const Params& p, LAS unsigned char* lds) {
;     ...
;       for (int k = 0; k < 128; ++k) { const float wv = wp[(size_t)k * NMODW]; const LAS float* sp = sc + (ks * 128 + k) * 20;
;         const f32x4 s0 = *(const LAS f32x4*)sp, s1 = *(const LAS f32x4*)(sp + 4), s2 = *(const LAS f32x4*)(sp + 8), s3 = *(const LAS f32x4*)(sp + 12); const float s16 = sp[16];
; #pragma unroll
;         for (int e = 0; e < 4; ++e) { a[e] += s0[e] * wv; a[4 + e] += s1[e] * wv; a[8 + e] += s2[e] * wv; a[12 + e] += s3[e] * wv; }
;         a[16] += s16 * wv; }
	v_mov_b32_e32 v114, v11
	v_mov_b32_e32 v115, v12
	v_mov_b32_e32 v98, v15
	v_mov_b32_e32 v99, v16
	v_mov_b32_e32 v108, v7
	v_mov_b32_e32 v109, v8
	v_mov_b32_e32 v116, v3
	v_mov_b32_e32 v117, v4
	v_mov_b32_e32 v7, v17
	v_mov_b32_e32 v11, v9
	v_mov_b32_e32 v3, v13
	s_waitcnt lgkmcnt(13)
	v_mov_b32_e32 v4, v100
	s_waitcnt lgkmcnt(12)
	v_mov_b32_e32 v8, v51
	v_mov_b32_e32 v9, v52
	s_waitcnt lgkmcnt(11)
	v_mov_b32_e32 v12, v55
	v_mov_b32_e32 v13, v56
	s_waitcnt lgkmcnt(10)
	v_mov_b32_e32 v16, v59
	v_mov_b32_e32 v17, v60
	s_waitcnt lgkmcnt(9)
	v_mov_b32_e32 v118, v63
	v_mov_b32_e32 v119, v64
	v_mov_b32_e32 v55, v53
	v_mov_b32_e32 v59, v57
	v_mov_b32_e32 v63, v61
	v_mov_b32_e32 v64, v101
	s_waitcnt lgkmcnt(8)
	v_mov_b32_e32 v52, v67
	v_mov_b32_e32 v53, v68
	s_waitcnt lgkmcnt(7)
	v_mov_b32_e32 v56, v71
	v_mov_b32_e32 v57, v72
	s_waitcnt lgkmcnt(6)
	v_mov_b32_e32 v60, v75
	v_mov_b32_e32 v61, v76
	s_waitcnt lgkmcnt(5)
	v_mov_b32_e32 v100, v79
	v_mov_b32_e32 v101, v80
	v_mov_b32_e32 v71, v69
	v_mov_b32_e32 v75, v73
	v_mov_b32_e32 v79, v77
	s_waitcnt lgkmcnt(4)
	v_mov_b32_e32 v80, v102
	s_waitcnt lgkmcnt(3)
	v_mov_b32_e32 v68, v83
	v_mov_b32_e32 v69, v84
	s_waitcnt lgkmcnt(2)
	v_mov_b32_e32 v72, v87
	v_mov_b32_e32 v73, v88
	s_waitcnt lgkmcnt(0)
	v_mov_b32_e32 v77, v96
	v_mov_b32_e32 v96, v103
	v_mov_b32_e32 v102, v91
	v_mov_b32_e32 v103, v92
	v_mov_b32_e32 v76, v95
	v_mov_b32_e32 v87, v85
	v_mov_b32_e32 v91, v89
	v_mov_b32_e32 v95, v93
	v_add_u32_e32 v49, 0x140, v49
	s_waitcnt vmcnt(11)
	v_fmac_f32_e32 v48, v130, v14
	v_pk_fma_f32 v[14:15], v[130:131], v[98:99], v[44:45] op_sel_hi:[0,1,1]
	v_pk_fma_f32 v[40:41], v[130:131], v[108:109], v[40:41] op_sel_hi:[0,1,1]
	v_pk_fma_f32 v[36:37], v[130:131], v[114:115], v[36:37] op_sel_hi:[0,1,1]
	v_pk_fma_f32 v[32:33], v[130:131], v[116:117], v[32:33] op_sel_hi:[0,1,1]
	v_pk_fma_f32 v[6:7], v[130:131], v[6:7], v[42:43] op_sel_hi:[0,1,1]
	v_pk_fma_f32 v[10:11], v[130:131], v[10:11], v[38:39] op_sel_hi:[0,1,1]
	v_pk_fma_f32 v[2:3], v[130:131], v[2:3], v[34:35] op_sel_hi:[0,1,1]
	v_pk_fma_f32 v[4:5], v[130:131], v[4:5], v[30:31] op_sel_hi:[0,1,1]
	s_waitcnt vmcnt(10)
	v_fmac_f32_e32 v48, v132, v50
	v_pk_fma_f32 v[8:9], v[132:133], v[8:9], v[14:15] op_sel_hi:[0,1,1]
	v_pk_fma_f32 v[12:13], v[132:133], v[12:13], v[40:41] op_sel_hi:[0,1,1]
	v_pk_fma_f32 v[14:15], v[132:133], v[16:17], v[36:37] op_sel_hi:[0,1,1]
	v_pk_fma_f32 v[16:17], v[132:133], v[118:119], v[32:33] op_sel_hi:[0,1,1]
	v_pk_fma_f32 v[6:7], v[132:133], v[54:55], v[6:7] op_sel_hi:[0,1,1]
	v_pk_fma_f32 v[10:11], v[132:133], v[58:59], v[10:11] op_sel_hi:[0,1,1]
	v_pk_fma_f32 v[2:3], v[132:133], v[62:63], v[2:3] op_sel_hi:[0,1,1]
	v_pk_fma_f32 v[4:5], v[132:133], v[64:65], v[4:5] op_sel_hi:[0,1,1]
	s_waitcnt vmcnt(9)
	v_fmac_f32_e32 v48, v134, v66
	v_pk_fma_f32 v[8:9], v[134:135], v[52:53], v[8:9] op_sel_hi:[0,1,1]
	v_pk_fma_f32 v[12:13], v[134:135], v[56:57], v[12:13] op_sel_hi:[0,1,1]
	v_pk_fma_f32 v[14:15], v[134:135], v[60:61], v[14:15] op_sel_hi:[0,1,1]
	v_pk_fma_f32 v[16:17], v[134:135], v[100:101], v[16:17] op_sel_hi:[0,1,1]
	v_pk_fma_f32 v[6:7], v[134:135], v[70:71], v[6:7] op_sel_hi:[0,1,1]
	v_pk_fma_f32 v[10:11], v[134:135], v[74:75], v[10:11] op_sel_hi:[0,1,1]
	v_pk_fma_f32 v[2:3], v[134:135], v[78:79], v[2:3] op_sel_hi:[0,1,1]
	v_pk_fma_f32 v[4:5], v[134:135], v[80:81], v[4:5] op_sel_hi:[0,1,1]
	s_waitcnt vmcnt(8)
	v_fmac_f32_e32 v48, v136, v82
	v_pk_fma_f32 v[44:45], v[136:137], v[68:69], v[8:9] op_sel_hi:[0,1,1]
	v_pk_fma_f32 v[40:41], v[136:137], v[72:73], v[12:13] op_sel_hi:[0,1,1]
	v_pk_fma_f32 v[36:37], v[136:137], v[102:103], v[14:15] op_sel_hi:[0,1,1]
	v_pk_fma_f32 v[32:33], v[136:137], v[76:77], v[16:17] op_sel_hi:[0,1,1]
	v_pk_fma_f32 v[42:43], v[136:137], v[86:87], v[6:7] op_sel_hi:[0,1,1]
	v_pk_fma_f32 v[38:39], v[136:137], v[90:91], v[10:11] op_sel_hi:[0,1,1]
	v_pk_fma_f32 v[34:35], v[136:137], v[94:95], v[2:3] op_sel_hi:[0,1,1]
	v_pk_fma_f32 v[30:31], v[136:137], v[96:97], v[4:5] op_sel_hi:[0,1,1]
	ds_read_b128 v[14:17], v49
	ds_read_b128 v[6:9], v49 offset:16
	ds_read_b128 v[10:13], v49 offset:32
	ds_read_b128 v[2:5], v49 offset:48
	ds_read2_b32 v[100:101], v49 offset0:16 offset1:36
	ds_read_b128 v[50:53], v49 offset:80
	ds_read_b128 v[54:57], v49 offset:96
	ds_read_b128 v[58:61], v49 offset:112
	ds_read_b128 v[62:65], v49 offset:128
	ds_read_b128 v[66:69], v49 offset:160
	ds_read_b128 v[70:73], v49 offset:176
	ds_read_b128 v[74:77], v49 offset:192
	ds_read_b128 v[78:81], v49 offset:208
	ds_read2_b32 v[102:103], v49 offset0:56 offset1:76
	ds_read_b128 v[82:85], v49 offset:240
	ds_read_b128 v[86:89], v49 offset:256
	ds_read_b128 v[90:93], v49 offset:272
	ds_read_b128 v[94:97], v49 offset:288
	s_waitcnt lgkmcnt(14)
	v_mov_b32_e32 v114, v11
	v_mov_b32_e32 v115, v12
	v_mov_b32_e32 v98, v15
	v_mov_b32_e32 v99, v16
	v_mov_b32_e32 v108, v7
	v_mov_b32_e32 v109, v8
	v_mov_b32_e32 v116, v3
	v_mov_b32_e32 v117, v4
	v_mov_b32_e32 v7, v17
	v_mov_b32_e32 v11, v9
	v_mov_b32_e32 v3, v13
	s_waitcnt lgkmcnt(13)
	v_mov_b32_e32 v4, v100
	s_waitcnt lgkmcnt(12)
	v_mov_b32_e32 v8, v51
	v_mov_b32_e32 v9, v52
	s_waitcnt lgkmcnt(11)
	v_mov_b32_e32 v12, v55
	v_mov_b32_e32 v13, v56
	s_waitcnt lgkmcnt(10)
	v_mov_b32_e32 v16, v59
	v_mov_b32_e32 v17, v60
	s_waitcnt lgkmcnt(9)
	v_mov_b32_e32 v118, v63
	v_mov_b32_e32 v119, v64
	v_mov_b32_e32 v55, v53
	v_mov_b32_e32 v59, v57
	v_mov_b32_e32 v63, v61
	v_mov_b32_e32 v64, v101
	s_waitcnt lgkmcnt(8)
	v_mov_b32_e32 v52, v67
	v_mov_b32_e32 v53, v68
	s_waitcnt lgkmcnt(7)
	v_mov_b32_e32 v56, v71
	v_mov_b32_e32 v57, v72
	s_waitcnt lgkmcnt(6)
	v_mov_b32_e32 v60, v75
	v_mov_b32_e32 v61, v76
	s_waitcnt lgkmcnt(5)
; #define LAS __attribute__((address_space(3)))
; DI void phase_prep(const Params& p, LAS unsigned char* lds) {
;     ...
;       for (int k = 0; k < 128; ++k) { const float wv = wp[(size_t)k * NMODW]; const LAS float* sp = sc + (ks * 128 + k) * 20;
;         const f32x4 s0 = *(const LAS f32x4*)sp, s1 = *(const LAS f32x4*)(sp + 4), s2 = *(const LAS f32x4*)(sp + 8), s3 = *(const LAS f32x4*)(sp + 12); const float s16 = sp[16];
; #pragma unroll
;         for (int e = 0; e < 4; ++e) { a[e] += s0[e] * wv; a[4 + e] += s1[e] * wv; a[8 + e] += s2[e] * wv; a[12 + e] += s3[e] * wv; }
;         a[16] += s16 * wv; }
	v_mov_b32_e32 v100, v79
	v_mov_b32_e32 v101, v80
	v_mov_b32_e32 v71, v69
	v_mov_b32_e32 v75, v73
	v_mov_b32_e32 v79, v77
	s_waitcnt lgkmcnt(4)
	v_mov_b32_e32 v80, v102
	s_waitcnt lgkmcnt(3)
	v_mov_b32_e32 v68, v83
	v_mov_b32_e32 v69, v84
	s_waitcnt lgkmcnt(2)
	v_mov_b32_e32 v72, v87
	v_mov_b32_e32 v73, v88
	s_waitcnt lgkmcnt(0)
	v_mov_b32_e32 v77, v96
	v_mov_b32_e32 v96, v103
	v_mov_b32_e32 v102, v91
	v_mov_b32_e32 v103, v92
	v_mov_b32_e32 v76, v95
	v_mov_b32_e32 v87, v85
	v_mov_b32_e32 v91, v89
	v_mov_b32_e32 v95, v93
	v_add_u32_e32 v49, 0x140, v49
	s_waitcnt vmcnt(7)
	v_fmac_f32_e32 v48, v138, v14
	v_pk_fma_f32 v[14:15], v[138:139], v[98:99], v[44:45] op_sel_hi:[0,1,1]
	v_pk_fma_f32 v[40:41], v[138:139], v[108:109], v[40:41] op_sel_hi:[0,1,1]
	v_pk_fma_f32 v[36:37], v[138:139], v[114:115], v[36:37] op_sel_hi:[0,1,1]
	v_pk_fma_f32 v[32:33], v[138:139], v[116:117], v[32:33] op_sel_hi:[0,1,1]
	v_pk_fma_f32 v[6:7], v[138:139], v[6:7], v[42:43] op_sel_hi:[0,1,1]
	v_pk_fma_f32 v[10:11], v[138:139], v[10:11], v[38:39] op_sel_hi:[0,1,1]
	v_pk_fma_f32 v[2:3], v[138:139], v[2:3], v[34:35] op_sel_hi:[0,1,1]
	v_pk_fma_f32 v[4:5], v[138:139], v[4:5], v[30:31] op_sel_hi:[0,1,1]
	s_waitcnt vmcnt(6)
	v_fmac_f32_e32 v48, v140, v50
	v_pk_fma_f32 v[8:9], v[140:141], v[8:9], v[14:15] op_sel_hi:[0,1,1]
	v_pk_fma_f32 v[12:13], v[140:141], v[12:13], v[40:41] op_sel_hi:[0,1,1]
	v_pk_fma_f32 v[14:15], v[140:141], v[16:17], v[36:37] op_sel_hi:[0,1,1]
	v_pk_fma_f32 v[16:17], v[140:141], v[118:119], v[32:33] op_sel_hi:[0,1,1]
	v_pk_fma_f32 v[6:7], v[140:141], v[54:55], v[6:7] op_sel_hi:[0,1,1]
	v_pk_fma_f32 v[10:11], v[140:141], v[58:59], v[10:11] op_sel_hi:[0,1,1]
	v_pk_fma_f32 v[2:3], v[140:141], v[62:63], v[2:3] op_sel_hi:[0,1,1]
	v_pk_fma_f32 v[4:5], v[140:141], v[64:65], v[4:5] op_sel_hi:[0,1,1]
	s_waitcnt vmcnt(5)
	v_fmac_f32_e32 v48, v142, v66
	v_pk_fma_f32 v[8:9], v[142:143], v[52:53], v[8:9] op_sel_hi:[0,1,1]
	v_pk_fma_f32 v[12:13], v[142:143], v[56:57], v[12:13] op_sel_hi:[0,1,1]
	v_pk_fma_f32 v[14:15], v[142:143], v[60:61], v[14:15] op_sel_hi:[0,1,1]
	v_pk_fma_f32 v[16:17], v[142:143], v[100:101], v[16:17] op_sel_hi:[0,1,1]
	v_pk_fma_f32 v[6:7], v[142:143], v[70:71], v[6:7] op_sel_hi:[0,1,1]
	v_pk_fma_f32 v[10:11], v[142:143], v[74:75], v[10:11] op_sel_hi:[0,1,1]
	v_pk_fma_f32 v[2:3], v[142:143], v[78:79], v[2:3] op_sel_hi:[0,1,1]
	v_pk_fma_f32 v[4:5], v[142:143], v[80:81], v[4:5] op_sel_hi:[0,1,1]
	s_waitcnt vmcnt(4)
	v_fmac_f32_e32 v48, v144, v82
	v_pk_fma_f32 v[44:45], v[144:145], v[68:69], v[8:9] op_sel_hi:[0,1,1]
	v_pk_fma_f32 v[40:41], v[144:145], v[72:73], v[12:13] op_sel_hi:[0,1,1]
	v_pk_fma_f32 v[36:37], v[144:145], v[102:103], v[14:15] op_sel_hi:[0,1,1]
	v_pk_fma_f32 v[32:33], v[144:145], v[76:77], v[16:17] op_sel_hi:[0,1,1]
	v_pk_fma_f32 v[42:43], v[144:145], v[86:87], v[6:7] op_sel_hi:[0,1,1]
	v_pk_fma_f32 v[38:39], v[144:145], v[90:91], v[10:11] op_sel_hi:[0,1,1]
	v_pk_fma_f32 v[34:35], v[144:145], v[94:95], v[2:3] op_sel_hi:[0,1,1]
	v_pk_fma_f32 v[30:31], v[144:145], v[96:97], v[4:5] op_sel_hi:[0,1,1]
	ds_read_b128 v[14:17], v49
	ds_read_b128 v[6:9], v49 offset:16
	ds_read_b128 v[10:13], v49 offset:32
	ds_read_b128 v[2:5], v49 offset:48
	ds_read2_b32 v[100:101], v49 offset0:16 offset1:36
	ds_read_b128 v[50:53], v49 offset:80
	ds_read_b128 v[54:57], v49 offset:96
	ds_read_b128 v[58:61], v49 offset:112
	ds_read_b128 v[62:65], v49 offset:128
	ds_read_b128 v[66:69], v49 offset:160
	ds_read_b128 v[70:73], v49 offset:176
	ds_read_b128 v[74:77], v49 offset:192
	ds_read_b128 v[78:81], v49 offset:208
	ds_read2_b32 v[102:103], v49 offset0:56 offset1:76
	ds_read_b128 v[82:85], v49 offset:240
	ds_read_b128 v[86:89], v49 offset:256
	ds_read_b128 v[90:93], v49 offset:272
	ds_read_b128 v[94:97], v49 offset:288
	s_waitcnt lgkmcnt(14)
	v_mov_b32_e32 v114, v11
	v_mov_b32_e32 v115, v12
	v_mov_b32_e32 v98, v15
	v_mov_b32_e32 v99, v16
	v_mov_b32_e32 v108, v7
	v_mov_b32_e32 v109, v8
	v_mov_b32_e32 v116, v3
	v_mov_b32_e32 v117, v4
	v_mov_b32_e32 v7, v17
	v_mov_b32_e32 v11, v9
	v_mov_b32_e32 v3, v13
	s_waitcnt lgkmcnt(13)
	v_mov_b32_e32 v4, v100
	s_waitcnt lgkmcnt(12)
	v_mov_b32_e32 v8, v51
	v_mov_b32_e32 v9, v52
	s_waitcnt lgkmcnt(11)
	v_mov_b32_e32 v12, v55
	v_mov_b32_e32 v13, v56
	s_waitcnt lgkmcnt(10)
	v_mov_b32_e32 v16, v59
	v_mov_b32_e32 v17, v60
	s_waitcnt lgkmcnt(9)
	v_mov_b32_e32 v118, v63
	v_mov_b32_e32 v119, v64
	v_mov_b32_e32 v55, v53
	v_mov_b32_e32 v59, v57
	v_mov_b32_e32 v63, v61
	v_mov_b32_e32 v64, v101
	s_waitcnt lgkmcnt(8)
	v_mov_b32_e32 v52, v67
	v_mov_b32_e32 v53, v68
	s_waitcnt lgkmcnt(7)
; #define LAS __attribute__((address_space(3)))
; DI void phase_prep(const Params& p, LAS unsigned char* lds) {
;     ...
;       for (int k = 0; k < 128; ++k) { const float wv = wp[(size_t)k * NMODW]; const LAS float* sp = sc + (ks * 128 + k) * 20;
;         const f32x4 s0 = *(const LAS f32x4*)sp, s1 = *(const LAS f32x4*)(sp + 4), s2 = *(const LAS f32x4*)(sp + 8), s3 = *(const LAS f32x4*)(sp + 12); const float s16 = sp[16];
; #pragma unroll
;         for (int e = 0; e < 4; ++e) { a[e] += s0[e] * wv; a[4 + e] += s1[e] * wv; a[8 + e] += s2[e] * wv; a[12 + e] += s3[e] * wv; }
;         a[16] += s16 * wv; }
; #pragma unroll
;       for (int r = 0; r < 17; ++r) red[(ks * 17 + r) * 64 + col] = a[r];
;       __syncthreads();
;       for (int i = tid; i < 17 * 64; i += 512) { const int r = i >> 6, cc = i & 63; float sum = p.b_ada[l * NMODW + col0 + cc];
; #pragma unroll
;         for (int q = 0; q < 8; ++q) sum += red[(q * 17 + r) * 64 + cc];
;         MOD[((size_t)l * 17 + r) * NMODW + col0 + cc] = sum; }
	v_mov_b32_e32 v56, v71
	v_mov_b32_e32 v57, v72
	s_waitcnt lgkmcnt(6)
	v_mov_b32_e32 v60, v75
	v_mov_b32_e32 v61, v76
	s_waitcnt lgkmcnt(5)
	v_mov_b32_e32 v100, v79
	v_mov_b32_e32 v101, v80
	v_mov_b32_e32 v71, v69
	v_mov_b32_e32 v75, v73
	v_mov_b32_e32 v79, v77
	s_waitcnt lgkmcnt(4)
	v_mov_b32_e32 v80, v102
	s_waitcnt lgkmcnt(3)
	v_mov_b32_e32 v68, v83
	v_mov_b32_e32 v69, v84
	s_waitcnt lgkmcnt(2)
	v_mov_b32_e32 v72, v87
	v_mov_b32_e32 v73, v88
	s_waitcnt lgkmcnt(0)
	v_mov_b32_e32 v77, v96
	v_mov_b32_e32 v96, v103
	v_mov_b32_e32 v102, v91
	v_mov_b32_e32 v103, v92
	v_mov_b32_e32 v76, v95
	v_mov_b32_e32 v87, v85
	v_mov_b32_e32 v91, v89
	v_mov_b32_e32 v95, v93
	v_add_u32_e32 v49, 0x140, v49
	s_waitcnt vmcnt(3)
	v_fmac_f32_e32 v48, v146, v14
	v_pk_fma_f32 v[14:15], v[146:147], v[98:99], v[44:45] op_sel_hi:[0,1,1]
	v_pk_fma_f32 v[40:41], v[146:147], v[108:109], v[40:41] op_sel_hi:[0,1,1]
	v_pk_fma_f32 v[36:37], v[146:147], v[114:115], v[36:37] op_sel_hi:[0,1,1]
	v_pk_fma_f32 v[32:33], v[146:147], v[116:117], v[32:33] op_sel_hi:[0,1,1]
	v_pk_fma_f32 v[6:7], v[146:147], v[6:7], v[42:43] op_sel_hi:[0,1,1]
	v_pk_fma_f32 v[10:11], v[146:147], v[10:11], v[38:39] op_sel_hi:[0,1,1]
	v_pk_fma_f32 v[2:3], v[146:147], v[2:3], v[34:35] op_sel_hi:[0,1,1]
	v_pk_fma_f32 v[4:5], v[146:147], v[4:5], v[30:31] op_sel_hi:[0,1,1]
	s_waitcnt vmcnt(2)
	v_fmac_f32_e32 v48, v148, v50
	v_pk_fma_f32 v[8:9], v[148:149], v[8:9], v[14:15] op_sel_hi:[0,1,1]
	v_pk_fma_f32 v[12:13], v[148:149], v[12:13], v[40:41] op_sel_hi:[0,1,1]
	v_pk_fma_f32 v[14:15], v[148:149], v[16:17], v[36:37] op_sel_hi:[0,1,1]
	v_pk_fma_f32 v[16:17], v[148:149], v[118:119], v[32:33] op_sel_hi:[0,1,1]
	v_pk_fma_f32 v[6:7], v[148:149], v[54:55], v[6:7] op_sel_hi:[0,1,1]
	v_pk_fma_f32 v[10:11], v[148:149], v[58:59], v[10:11] op_sel_hi:[0,1,1]
	v_pk_fma_f32 v[2:3], v[148:149], v[62:63], v[2:3] op_sel_hi:[0,1,1]
	v_pk_fma_f32 v[4:5], v[148:149], v[64:65], v[4:5] op_sel_hi:[0,1,1]
	s_waitcnt vmcnt(1)
	v_fmac_f32_e32 v48, v150, v66
	v_pk_fma_f32 v[8:9], v[150:151], v[52:53], v[8:9] op_sel_hi:[0,1,1]
	v_pk_fma_f32 v[12:13], v[150:151], v[56:57], v[12:13] op_sel_hi:[0,1,1]
	v_pk_fma_f32 v[14:15], v[150:151], v[60:61], v[14:15] op_sel_hi:[0,1,1]
	v_pk_fma_f32 v[16:17], v[150:151], v[100:101], v[16:17] op_sel_hi:[0,1,1]
	v_pk_fma_f32 v[6:7], v[150:151], v[70:71], v[6:7] op_sel_hi:[0,1,1]
	v_pk_fma_f32 v[10:11], v[150:151], v[74:75], v[10:11] op_sel_hi:[0,1,1]
	v_pk_fma_f32 v[2:3], v[150:151], v[78:79], v[2:3] op_sel_hi:[0,1,1]
	v_pk_fma_f32 v[4:5], v[150:151], v[80:81], v[4:5] op_sel_hi:[0,1,1]
	s_waitcnt vmcnt(0)
	v_fmac_f32_e32 v48, v152, v82
	v_pk_fma_f32 v[44:45], v[152:153], v[68:69], v[8:9] op_sel_hi:[0,1,1]
	v_pk_fma_f32 v[40:41], v[152:153], v[72:73], v[12:13] op_sel_hi:[0,1,1]
	v_pk_fma_f32 v[36:37], v[152:153], v[102:103], v[14:15] op_sel_hi:[0,1,1]
	v_pk_fma_f32 v[32:33], v[152:153], v[76:77], v[16:17] op_sel_hi:[0,1,1]
	v_pk_fma_f32 v[42:43], v[152:153], v[86:87], v[6:7] op_sel_hi:[0,1,1]
	v_pk_fma_f32 v[38:39], v[152:153], v[90:91], v[10:11] op_sel_hi:[0,1,1]
	v_pk_fma_f32 v[34:35], v[152:153], v[94:95], v[2:3] op_sel_hi:[0,1,1]
	v_pk_fma_f32 v[30:31], v[152:153], v[96:97], v[4:5] op_sel_hi:[0,1,1]
	s_mul_i32 s5, s4, 0x2400
	s_add_i32 s5, s5, s6
	v_or_b32_e32 v2, s5, v18
	s_mul_hi_i32 s8, s4, 0x99000
	s_mul_i32 s9, s4, 0x99000
	s_lshl_b64 s[4:5], s[6:7], 2
	v_readlane_b32 s36, v253, 10
	s_add_u32 s4, s9, s4
	v_ashrrev_i32_e32 v3, 31, v2
	v_readlane_b32 s46, v253, 20
	v_readlane_b32 s47, v253, 21
	s_addc_u32 s5, s8, s5
	v_lshl_add_u64 v[4:5], v[24:25], 0, s[4:5]
	v_lshl_add_u64 v[2:3], v[2:3], 2, s[46:47]
	s_mov_b64 s[4:5], 0
	v_mov_b32_e32 v6, v46
	v_mov_b32_e32 v7, v19
	ds_write2st64_b32 v47, v48, v44 offset1:1
	ds_write2st64_b32 v47, v45, v43 offset0:2 offset1:3
	ds_write2st64_b32 v47, v42, v40 offset0:4 offset1:5
	ds_write2st64_b32 v47, v41, v39 offset0:6 offset1:7
	ds_write2st64_b32 v47, v38, v36 offset0:8 offset1:9
	ds_write2st64_b32 v47, v37, v35 offset0:10 offset1:11
	ds_write2st64_b32 v47, v34, v32 offset0:12 offset1:13
	ds_write2st64_b32 v47, v33, v31 offset0:14 offset1:15
	ds_write_b32 v47, v30 offset:4096
	s_waitcnt lgkmcnt(0)
	s_barrier
	v_readlane_b32 s37, v253, 11
	v_readlane_b32 s38, v253, 12
	v_readlane_b32 s39, v253, 13
	v_readlane_b32 s40, v253, 14
	v_readlane_b32 s41, v253, 15
	v_readlane_b32 s42, v253, 16
	v_readlane_b32 s43, v253, 17
	v_readlane_b32 s44, v253, 18
	v_readlane_b32 s45, v253, 19
	v_readlane_b32 s48, v253, 22
	v_readlane_b32 s49, v253, 23
	v_readlane_b32 s50, v253, 24
	v_readlane_b32 s51, v253, 25
